# v8 + nt on the P0 bf16 weight stores (8 global_store_dwordx4)
# speedup vs baseline: 1.0061x; 1.0026x over previous
.Lp0_nomul_pa:
	v_cvt_pk_bf16_f32 v12, v36, v40
	v_cvt_pk_bf16_f32 v13, v44, v48
	v_cvt_pk_bf16_f32 v14, v52, v56
	v_cvt_pk_bf16_f32 v15, v60, v64
	v_cvt_pk_bf16_f32 v16, v37, v41
	v_cvt_pk_bf16_f32 v17, v45, v49
	v_cvt_pk_bf16_f32 v18, v53, v57
	v_cvt_pk_bf16_f32 v19, v61, v65
	v_cvt_pk_bf16_f32 v20, v38, v42
	v_cvt_pk_bf16_f32 v21, v46, v50
	v_cvt_pk_bf16_f32 v22, v54, v58
	v_cvt_pk_bf16_f32 v23, v62, v66
	v_cvt_pk_bf16_f32 v24, v39, v43
	v_cvt_pk_bf16_f32 v25, v47, v51
	v_cvt_pk_bf16_f32 v26, v55, v59
	v_cvt_pk_bf16_f32 v27, v63, v67
	ds_write_b128 v4, v[12:15] offset:0
	ds_write_b128 v4, v[16:19] offset:128
	ds_write_b128 v4, v[20:23] offset:256
	ds_write_b128 v4, v[24:27] offset:384
	s_waitcnt lgkmcnt(0)
	ds_read_b128 v[12:15], v5 offset:0
	ds_read_b128 v[16:19], v6 offset:1024
	ds_read_b128 v[20:23], v7 offset:2048
	ds_read_b128 v[24:27], v8 offset:3072
	s_waitcnt lgkmcnt(0)
	global_store_dwordx4 v9, v[12:15], s[46:47] nt
	global_store_dwordx4 v9, v[16:19], s[46:47] offset:1024 nt
	global_store_dwordx4 v9, v[20:23], s[46:47] offset:2048 nt
	global_store_dwordx4 v9, v[24:27], s[46:47] offset:3072 nt

.Lp0_nomul_pb:
	v_cvt_pk_bf16_f32 v12, v76, v80
	v_cvt_pk_bf16_f32 v13, v84, v88
	v_cvt_pk_bf16_f32 v14, v92, v96
	v_cvt_pk_bf16_f32 v15, v100, v104
	v_cvt_pk_bf16_f32 v16, v77, v81
	v_cvt_pk_bf16_f32 v17, v85, v89
	v_cvt_pk_bf16_f32 v18, v93, v97
	v_cvt_pk_bf16_f32 v19, v101, v105
	v_cvt_pk_bf16_f32 v20, v78, v82
	v_cvt_pk_bf16_f32 v21, v86, v90
	v_cvt_pk_bf16_f32 v22, v94, v98
	v_cvt_pk_bf16_f32 v23, v102, v106
	v_cvt_pk_bf16_f32 v24, v79, v83
	v_cvt_pk_bf16_f32 v25, v87, v91
	v_cvt_pk_bf16_f32 v26, v95, v99
	v_cvt_pk_bf16_f32 v27, v103, v107
	ds_write_b128 v4, v[12:15] offset:0
	ds_write_b128 v4, v[16:19] offset:128
	ds_write_b128 v4, v[20:23] offset:256
	ds_write_b128 v4, v[24:27] offset:384
	s_waitcnt lgkmcnt(0)
	ds_read_b128 v[12:15], v5 offset:0
	ds_read_b128 v[16:19], v6 offset:1024
	ds_read_b128 v[20:23], v7 offset:2048
	ds_read_b128 v[24:27], v8 offset:3072
	s_waitcnt lgkmcnt(0)
	global_store_dwordx4 v9, v[12:15], s[54:55] nt
	global_store_dwordx4 v9, v[16:19], s[54:55] offset:1024 nt
	global_store_dwordx4 v9, v[20:23], s[54:55] offset:2048 nt
	global_store_dwordx4 v9, v[24:27], s[54:55] offset:3072 nt
